# v101 with code after phase0 shifted by 56 bytes (placement variant)
# speedup vs baseline: 1.0735x; 1.0064x over previous
.Lp0_bh:
	ds_read2st64_b32 v[4:5], v40 offset0:128 offset1:131
	ds_read2st64_b32 v[6:7], v40 offset0:134 offset1:137
	ds_read2st64_b32 v[8:9], v40 offset0:140 offset1:143
	ds_read2st64_b32 v[18:19], v40 offset0:146 offset1:149
	ds_read2st64_b32 v[20:21], v40 offset0:152 offset1:155
	ds_read2st64_b32 v[22:23], v40 offset0:158 offset1:161
	ds_read2st64_b32 v[24:25], v40 offset0:164 offset1:167
	ds_read2st64_b32 v[26:27], v40 offset0:170 offset1:173
	ds_read2st64_b32 v[28:29], v40 offset0:176 offset1:179
	ds_read2st64_b32 v[30:31], v40 offset0:182 offset1:185
	ds_read_b32 v32, v40 offset:48128
	v_add_u32_e32 v2, v2, v38
	v_ashrrev_i32_e32 v3, 31, v2
	v_lshl_add_u64 v[2:3], v[2:3], 2, s[16:17]
	s_waitcnt vmcnt(0) lgkmcnt(0)
	v_add_f32_e32 v4, v149, v4
	v_add_f32_e32 v4, v4, v5
	v_add_f32_e32 v4, v4, v6
	v_add_f32_e32 v4, v4, v7
	v_add_f32_e32 v4, v4, v8
	v_add_f32_e32 v4, v4, v9
	v_add_f32_e32 v4, v4, v18
	v_add_f32_e32 v4, v4, v19
	v_add_f32_e32 v4, v4, v20
	v_add_f32_e32 v4, v4, v21
	v_add_f32_e32 v4, v4, v22
	v_add_f32_e32 v4, v4, v23
	v_add_f32_e32 v4, v4, v24
	v_add_f32_e32 v4, v4, v25
	v_add_f32_e32 v4, v4, v26
	v_add_f32_e32 v4, v4, v27
	v_add_f32_e32 v4, v4, v28
	v_add_f32_e32 v4, v4, v29
	v_add_f32_e32 v4, v4, v30
	v_add_f32_e32 v4, v4, v31
	v_add_f32_e32 v4, v4, v32
	flat_store_dword v[2:3], v4
	s_branch .LBB0_13
	s_nop 0
	s_nop 0
	s_nop 0
	s_nop 0
	s_nop 0
	s_nop 0
	s_nop 0
	s_nop 0
	s_nop 0
	s_nop 0
	s_nop 0
	s_nop 0
	s_nop 0
	s_nop 0
